# v57 + RWKV next-chunk triangle tiles: branch maze replaced by three straight role paths with packed dword LDS writes
# speedup vs baseline: 1.0187x; 1.0120x over previous
; #define LAS __attribute__((address_space(3)))
; __device__ __forceinline__ bf16_t f2bf(float f) { const __bf16 r = (__bf16)f; bf16_t u; __builtin_memcpy(&u, &r, 2); return u; }
; __device__ __forceinline__ f32x4 mfma16(bf16x8 a, bf16x8 b, f32x4 c) { return __builtin_amdgcn_mfma_f32_16x16x32_bf16(a, b, c, 0, 0, 0); }
; __device__ __forceinline__ void rwkv_chunk_item(const P& p, const Ctx& c, int seg, int w, bool save) {
;     ...
;     auto gtile = [&](int pb, int l15, int quad) {
;         LAS bf16_t* EA = (LAS bf16_t*)(OB + pb * OPB + O_EA); LAS bf16_t* EB = (LAS bf16_t*)(OB + pb * OPB + O_EB);
;         LAS bf16_t* MT1 = (LAS bf16_t*)(OB + pb * OPB + O_MT1); LAS bf16_t* NT = (LAS bf16_t*)(OB + pb * OPB + O_NT); LAS float* MABT = (LAS float*)(OB + pb * OPB + O_MABT);
;         const int sb = c.wv >> 1, tb = c.wv & 1; f32x4 g = (f32x4){0.f, 0.f, 0.f, 0.f};
; #pragma unroll
;         for (int kk = 0; kk < 2; ++kk) g = mfma16(*(const LAS bf16x8*)(EB + (sb * 16 + l15) * 72 + kk * 32 + quad * 8), *(const LAS bf16x8*)(EA + (tb * 16 + l15) * 72 + kk * 32 + quad * 8), g);
; #pragma unroll
;         for (int jj = 0; jj < 4; ++jj) { const int s2 = quad * 4 + jj, tt = l15; const float v = g[jj];
;             if (tb == 0) { const float m = (s2 < tt) ? v : 0.f; if (sb == 0) { MABT[s2 * 20 + tt] = m; MT1[tt * 40 + s2] = 0; } else MT1[tt * 40 + 16 + s2] = f2bf(m); }
;             else { const float m = (s2 <= tt) ? v : 0.f; NT[tt * 40 + sb * 16 + s2] = f2bf(m); } } };
;     ...
; #pragma unroll
;         for (int x = 0; x < 2; ++x) { const int ti = c.wv * 2 + x, mt = ti >> 2, nt = ti & 3;
;             S[x] = mfma16(*(const LAS bf16x8*)(UV + (mt * 16 + l15) * 40 + quad * 8), *(const LAS bf16x8*)(EBT + (nt * 16 + l15) * 40 + quad * 8), S[x]);
;             const float gt = GT[nt * 16 + l15];
; #pragma unroll
;             for (int jj = 0; jj < 4; ++jj) S[x][jj] *= gt; }
;         simg(l15, quad);
;         if (c.wv < 4 && ch + 1 < SEGT / 16) gtile(pb ^ 1, l15, quad);
.LBB0_900:
	v_add_u32_e32 v22, s45, v82
	v_lshl_add_u32 v2, v45, 1, s88
	v_mad_u64_u32 v[22:23], s[2:3], v22, s64, v[2:3]
	ds_read_b128 v[22:25], v22 offset:14336
	v_add_u32_e32 v42, s34, v82
	v_mad_u64_u32 v[38:39], s[2:3], v42, s64, v[2:3]
	ds_read_b128 v[38:41], v38 offset:9216
	v_add_u32_e32 v124, s66, v82
	v_mad_u64_u32 v[124:125], s[2:3], v124, s64, v[2:3]
	ds_read_b128 v[124:127], v124 offset:9216
	v_lshl_add_u32 v128, v42, 2, s88
	v_add_u32_e32 v128, 0x5800, v128
	ds_read2_b32 v[42:43], v128 offset0:192 offset1:208
	s_waitcnt lgkmcnt(2)
	v_mfma_f32_16x16x32_bf16 v[6:9], v[22:25], v[38:41], v[6:9]
	s_waitcnt lgkmcnt(0)
	v_mfma_f32_16x16x32_bf16 v[10:13], v[22:25], v[124:127], v[10:13]
	v_mov_b32_e32 v2, v43
	v_lshlrev_b32_e32 v38, 2, v83
	s_nop 7
	v_pk_mul_f32 v[6:7], v[42:43], v[6:7] op_sel_hi:[0,1]
	s_nop 4
	v_pk_mul_f32 v[10:11], v[2:3], v[10:11] op_sel_hi:[0,1]
	v_pk_mul_f32 v[12:13], v[2:3], v[12:13] op_sel_hi:[0,1]
	v_add_u32_e32 v2, s45, v38
	v_lshlrev_b32_e32 v22, 1, v82
	v_mul_lo_u32 v2, v2, s63
	v_pk_mul_f32 v[8:9], v[42:43], v[8:9] op_sel_hi:[0,1]
	v_add3_u32 v2, s40, v22, v2
	v_and_b32_e32 v140, 1, v82
	v_cmp_ne_u32_e64 s[2:3], 0, v140
	v_mov_b32_e32 v141, 0x5040100
	v_mov_b32_e32 v142, 0x3020706
	v_mul_u32_u24_e32 v140, 0x11e, v140
	v_cndmask_b32_e64 v141, v141, v142, s[2:3]
	v_add_u32_e32 v140, v2, v140
	v_cvt_pk_bf16_f32 v22, v6, v8
	v_cvt_pk_bf16_f32 v23, v7, v9
	v_cvt_pk_bf16_f32 v142, v10, v12
	v_cvt_pk_bf16_f32 v143, v11, v13
	v_mov_b32_dpp v144, v22 quad_perm:[1,0,3,2] row_mask:0xf bank_mask:0xf bound_ctrl:1
	v_mov_b32_dpp v145, v23 quad_perm:[1,0,3,2] row_mask:0xf bank_mask:0xf bound_ctrl:1
	v_mov_b32_dpp v146, v142 quad_perm:[1,0,3,2] row_mask:0xf bank_mask:0xf bound_ctrl:1
	v_mov_b32_dpp v147, v143 quad_perm:[1,0,3,2] row_mask:0xf bank_mask:0xf bound_ctrl:1
	v_perm_b32 v22, v144, v22, v141
	v_perm_b32 v23, v145, v23, v141
	v_perm_b32 v142, v146, v142, v141
	v_perm_b32 v143, v147, v143, v141
	s_or_b64 s[2:3], s[56:57], s[4:5]
	ds_write_b32 v140, v22 offset:47104
	ds_write_b32 v140, v23 offset:47248
	ds_write_b32 v140, v142 offset:47136
	s_and_b64 vcc, exec, s[2:3]
	ds_write_b32 v140, v143 offset:47280
	s_cbranch_vccnz .LBB0_929
	s_xor_b32 s2, s87, 1
	s_mulk_i32 s2, 0x5c00
	v_add_u32_e32 v2, s67, v82
	s_add_i32 s4, s2, 0
	v_mul_lo_u32 v2, v2, s63
	v_lshlrev_b32_e32 v22, 1, v45
	v_add_u32_e32 v23, s83, v82
	v_add3_u32 v2, s4, v2, v22
	v_mul_lo_u32 v23, v23, s63
	v_add3_u32 v39, s4, v23, v22
	ds_read_b128 v[22:25], v2 offset:4608
	ds_read_b128 v[40:43], v39
	ds_read_b128 v[124:127], v2 offset:4672
	ds_read_b128 v[86:89], v39 offset:64
	s_waitcnt lgkmcnt(2)
	v_mfma_f32_16x16x32_bf16 v[22:25], v[22:25], v[40:43], 0
	v_add_u32_e32 v39, s4, v84
	v_add_u32_e32 v2, s84, v39
	s_waitcnt lgkmcnt(0)
	v_mfma_f32_16x16x32_bf16 v[22:25], v[124:127], v[86:89], v[22:25]
	v_lshl_add_u32 v40, v38, 1, v2
	v_lshl_add_u32 v41, v38, 1, v39
	v_lshl_add_u32 v2, v82, 2, s4
	v_or_b32_e32 v42, 1, v38
	v_or_b32_e32 v43, 2, v38
	v_or_b32_e32 v140, 3, v38
	s_and_b64 vcc, exec, s[72:73]
	s_nop 3
	s_cbranch_vccz .Lrw_mb_notA
	v_cmp_le_i32_e32 vcc, v38, v82
	s_nop 1
	v_cndmask_b32_e32 v22, 0, v22, vcc
	v_cmp_le_i32_e32 vcc, v42, v82
	s_nop 1
	v_cndmask_b32_e32 v23, 0, v23, vcc
	v_cmp_le_i32_e32 vcc, v43, v82
	s_nop 1
	v_cndmask_b32_e32 v24, 0, v24, vcc
	v_cmp_le_i32_e32 vcc, v140, v82
	s_nop 1
	v_cndmask_b32_e32 v25, 0, v25, vcc
	v_cvt_pk_bf16_f32 v22, v22, v23
	v_cvt_pk_bf16_f32 v24, v24, v25
	ds_write_b32 v40, v22 offset:20736
	ds_write_b32 v40, v24 offset:20740
	s_branch .LBB0_929
.Lrw_mb_notA:
	v_cmp_lt_i32_e32 vcc, v38, v82
	s_nop 1
	v_cndmask_b32_e32 v22, 0, v22, vcc
	v_cmp_lt_i32_e32 vcc, v42, v82
	s_nop 1
	v_cndmask_b32_e32 v23, 0, v23, vcc
	v_cmp_lt_i32_e32 vcc, v43, v82
	s_nop 1
	v_cndmask_b32_e32 v24, 0, v24, vcc
	v_cmp_lt_i32_e32 vcc, v140, v82
	s_nop 1
	v_cndmask_b32_e32 v25, 0, v25, vcc
	s_and_b64 vcc, exec, s[74:75]
	s_cbranch_vccz .Lrw_mb_roleC
	v_cvt_pk_bf16_f32 v22, v22, v23
	v_cvt_pk_bf16_f32 v24, v24, v25
	ds_write_b32 v41, v22 offset:19488
	ds_write_b32 v41, v24 offset:19492
	s_branch .LBB0_929
.Lrw_mb_roleC:
	v_mad_u64_u32 v[42:43], s[2:3], v38, s64, v[2:3]
	ds_write_b32 v42, v22 offset:22016
	ds_write_b32 v42, v23 offset:22096
	ds_write_b32 v42, v24 offset:22176
	ds_write_b32 v42, v25 offset:22256
	ds_write_b32 v41, v5 offset:19456
	ds_write_b32 v41, v5 offset:19460
